# in_proj epilogue: global_store with SGPR base + 32-bit VGPR offset (saddr form) instead of 64-bit VGPR addresses; 32-bit address math
# speedup vs baseline: 1.0353x; 1.0047x over previous
; #define PG8_STAGE(bufoff, gbase, voff) do { _Pragma("unroll") for (int _i = 0; _i < 2; ++_i) \
;         __builtin_amdgcn_global_load_lds((const unsigned*)((const char*)(gbase) + (voff)[_i]), (LAS unsigned*)(lds + (bufoff) + ldsw + _i * 8192), 16, 0, 0); } while (0)
; #define PG8_LDA(dst, b, h) do { _Pragma("unroll") for (int m = 0; m < 4; ++m) _Pragma("unroll") for (int k = 0; k < 2; ++k) dst[m][k] = *(const LAS bf16x8*)(lds + PG8_SA(b, h) + aoff + m * 2048 + k * 1024); } while (0)
; #define PG8_LDB(dst, b, h) do { _Pragma("unroll") for (int n = 0; n < 2; ++n) _Pragma("unroll") for (int k = 0; k < 2; ++k) dst[n][k] = *(const LAS bf16x8*)(lds + PG8_SB(b, h) + boff + n * 2048 + k * 1024); } while (0)
; #define PG8_MMA(ai, bj, At, Bt) do { __builtin_amdgcn_s_setprio(1); _Pragma("unroll") for (int m = 0; m < 4; ++m) _Pragma("unroll") for (int n = 0; n < 2; ++n) _Pragma("unroll") for (int k = 0; k < 2; ++k) \
;         acc[ai][bj][m][n] = __builtin_amdgcn_mfma_f32_16x16x32_bf16(Bt[n][k], At[m][k], acc[ai][bj][m][n], 0, 0, 0); __builtin_amdgcn_s_setprio(0); } while (0)
; #define PG8_WAIT_V(n) asm volatile("s_waitcnt vmcnt(" #n ")" ::: "memory")
; #define PG8_WAIT_L(n) asm volatile("s_waitcnt lgkmcnt(" #n ")" ::: "memory")
; #define PG8_BAR __builtin_amdgcn_s_barrier()
; #define PG8_SCHED __builtin_amdgcn_sched_barrier(0)
; template <class Epi>
; __device__ __forceinline__ void gemm_phase(LAS unsigned char* lds, const Gemm g, const StaticOrder& S, const Epi& E) {
;     ...
;             const char* a1 = cA + (size_t)(t + 1) * kstep;
;             const char* a2 = last ? nA : cA + (size_t)(t + 2) * kstep; const char* b2 = last ? nB : cB + (size_t)(t + 2) * kstep;
;             const char* a3 = a2 + kstep; const char* b3 = b2 + kstep;
;             PG8_LDB(B0, 0, 0); PG8_SCHED; PG8_LDA(At, 0, 0); PG8_STAGE(PG8_SA(1, 1), a1 + hA, voffA);
;             PG8_WAIT_L(8); PG8_BAR; PG8_WAIT_L(0); PG8_MMA(0, 0, At, B0); PG8_BAR; PG8_SCHED;
;             PG8_LDB(B1, 0, 1); PG8_STAGE(PG8_SB(0, 0), b2, voffB);
;             PG8_BAR; PG8_WAIT_L(0); PG8_MMA(0, 1, At, B1); PG8_BAR;
;             PG8_LDA(At, 0, 1); PG8_STAGE(PG8_SA(0, 0), a2, voffA);
;             PG8_BAR; PG8_WAIT_L(0); PG8_MMA(1, 0, At, B0); PG8_BAR; PG8_SCHED;
;             PG8_STAGE(PG8_SB(0, 1), b2 + hB, voffB);
;             PG8_WAIT_V(6); PG8_BAR; PG8_MMA(1, 1, At, B1); PG8_BAR;
.LBB0_623:
	s_add_u32 s48, s46, 0xfffc0080
	s_addc_u32 s49, s47, -1
	s_add_i32 s67, 0, 0x10000
	v_add_u32_e32 v151, s67, v143
	ds_read_b128 v[156:159], v151
	ds_read_b128 v[160:163], v151 offset:1024
	ds_read_b128 v[164:167], v151 offset:2048
	ds_read_b128 v[168:171], v151 offset:3072
	s_cmp_eq_u32 s66, 12
	s_cselect_b32 s51, s23, s49
	s_cselect_b32 s50, s62, s48
	s_cselect_b32 s49, s15, s65
	s_cselect_b32 s48, s63, s64
	v_lshl_add_u64 v[210:211], s[46:47], 0, v[144:145]
	s_add_i32 m0, s53, 0xc000
	ds_read_b128 v[172:175], v149
	ds_read_b128 v[176:179], v149 offset:1024
	ds_read_b128 v[180:183], v149 offset:2048
	ds_read_b128 v[184:187], v149 offset:3072
	ds_read_b128 v[188:191], v149 offset:4096
	ds_read_b128 v[192:195], v149 offset:5120
	ds_read_b128 v[202:205], v149 offset:6144
	ds_read_b128 v[206:209], v149 offset:7168
	global_load_lds_dwordx4 v[210:211], off
	v_lshl_add_u64 v[210:211], s[46:47], 0, v[146:147]
	s_add_i32 m0, s53, 0xe000
	s_nop 0
	global_load_lds_dwordx4 v[210:211], off
	s_waitcnt lgkmcnt(8)
	s_barrier
	s_waitcnt lgkmcnt(0)
	s_setprio 1
	s_waitcnt lgkmcnt(0)
	v_mfma_f32_16x16x32_bf16 v[126:129], v[156:159], v[172:175], v[126:129]
	v_mfma_f32_16x16x32_bf16 v[122:125], v[164:167], v[172:175], v[122:125]
	v_mfma_f32_16x16x32_bf16 v[118:121], v[156:159], v[180:183], v[118:121]
	v_mfma_f32_16x16x32_bf16 v[110:113], v[164:167], v[180:183], v[110:113]
	v_mfma_f32_16x16x32_bf16 v[102:105], v[156:159], v[188:191], v[102:105]
	v_mfma_f32_16x16x32_bf16 v[94:97], v[164:167], v[188:191], v[94:97]
	v_mfma_f32_16x16x32_bf16 v[86:89], v[156:159], v[202:205], v[86:89]
	v_mfma_f32_16x16x32_bf16 v[78:81], v[164:167], v[202:205], v[78:81]
	v_mfma_f32_16x16x32_bf16 v[126:129], v[160:163], v[176:179], v[126:129]
	v_mfma_f32_16x16x32_bf16 v[122:125], v[168:171], v[176:179], v[122:125]
	v_mfma_f32_16x16x32_bf16 v[118:121], v[160:163], v[184:187], v[118:121]
	v_mfma_f32_16x16x32_bf16 v[110:113], v[168:171], v[184:187], v[110:113]
	v_mfma_f32_16x16x32_bf16 v[102:105], v[160:163], v[192:195], v[102:105]
	v_mfma_f32_16x16x32_bf16 v[94:97], v[168:171], v[192:195], v[94:97]
	v_mfma_f32_16x16x32_bf16 v[86:89], v[160:163], v[206:209], v[86:89]
	v_mfma_f32_16x16x32_bf16 v[78:81], v[168:171], v[206:209], v[78:81]
	s_setprio 0
	s_barrier
	s_add_i32 s70, 0, 0x14000
	s_add_i32 s67, s67, s33
	v_add_u32_e32 v151, s70, v143
	v_lshl_add_u64 v[226:227], s[48:49], 0, v[0:1]
	s_mov_b32 m0, s67
	ds_read_b128 v[210:213], v151
	ds_read_b128 v[214:217], v151 offset:1024
	ds_read_b128 v[218:221], v151 offset:2048
	ds_read_b128 v[222:225], v151 offset:3072
	global_load_lds_dwordx4 v[226:227], off
	v_lshl_add_u64 v[240:241], s[48:49], 0, v[134:135]
	s_add_i32 m0, s67, 0x2000
	s_nop 0
	global_load_lds_dwordx4 v[240:241], off
	s_barrier
	s_waitcnt lgkmcnt(0)
	s_setprio 1
	s_waitcnt lgkmcnt(0)
	v_mfma_f32_16x16x32_bf16 v[114:117], v[210:213], v[172:175], v[114:117]
	v_mfma_f32_16x16x32_bf16 v[106:109], v[218:221], v[172:175], v[106:109]
	v_mfma_f32_16x16x32_bf16 v[98:101], v[210:213], v[180:183], v[98:101]
	v_mfma_f32_16x16x32_bf16 v[90:93], v[218:221], v[180:183], v[90:93]
	v_mfma_f32_16x16x32_bf16 v[82:85], v[210:213], v[188:191], v[82:85]
	v_mfma_f32_16x16x32_bf16 v[74:77], v[218:221], v[188:191], v[74:77]
	v_mfma_f32_16x16x32_bf16 v[70:73], v[210:213], v[202:205], v[70:73]
	v_mfma_f32_16x16x32_bf16 v[66:69], v[218:221], v[202:205], v[66:69]
	v_mfma_f32_16x16x32_bf16 v[114:117], v[214:217], v[176:179], v[114:117]
	v_mfma_f32_16x16x32_bf16 v[106:109], v[222:225], v[176:179], v[106:109]
	v_mfma_f32_16x16x32_bf16 v[98:101], v[214:217], v[184:187], v[98:101]
	v_mfma_f32_16x16x32_bf16 v[90:93], v[222:225], v[184:187], v[90:93]
	v_mfma_f32_16x16x32_bf16 v[82:85], v[214:217], v[192:195], v[82:85]
	v_mfma_f32_16x16x32_bf16 v[74:77], v[222:225], v[192:195], v[74:77]
	v_mfma_f32_16x16x32_bf16 v[70:73], v[214:217], v[206:209], v[70:73]
	v_mfma_f32_16x16x32_bf16 v[66:69], v[222:225], v[206:209], v[66:69]
	s_setprio 0
	s_mov_b32 m0, s53
	v_lshl_add_u64 v[242:243], s[50:51], 0, v[130:131]
	s_barrier
	ds_read_b128 v[172:175], v149 offset:16384
	ds_read_b128 v[176:179], v149 offset:17408
	ds_read_b128 v[180:183], v149 offset:18432
	ds_read_b128 v[184:187], v149 offset:19456
	ds_read_b128 v[188:191], v149 offset:20480
	ds_read_b128 v[192:195], v149 offset:21504
	ds_read_b128 v[202:205], v149 offset:22528
	ds_read_b128 v[206:209], v149 offset:23552
	global_load_lds_dwordx4 v[242:243], off
	v_lshl_add_u64 v[244:245], s[50:51], 0, v[132:133]
	s_mov_b32 m0, s54
	s_nop 0
	global_load_lds_dwordx4 v[244:245], off
	s_barrier
	s_waitcnt lgkmcnt(0)
	s_setprio 1
	s_waitcnt lgkmcnt(0)
	v_mfma_f32_16x16x32_bf16 v[62:65], v[156:159], v[172:175], v[62:65]
	v_mfma_f32_16x16x32_bf16 v[58:61], v[164:167], v[172:175], v[58:61]
	v_mfma_f32_16x16x32_bf16 v[54:57], v[156:159], v[180:183], v[54:57]
	v_mfma_f32_16x16x32_bf16 v[46:49], v[164:167], v[180:183], v[46:49]
	v_mfma_f32_16x16x32_bf16 v[38:41], v[156:159], v[188:191], v[38:41]
	v_mfma_f32_16x16x32_bf16 v[30:33], v[164:167], v[188:191], v[30:33]
	v_mfma_f32_16x16x32_bf16 v[22:25], v[156:159], v[202:205], v[22:25]
	v_mfma_f32_16x16x32_bf16 v[14:17], v[164:167], v[202:205], v[14:17]
	v_mfma_f32_16x16x32_bf16 v[62:65], v[160:163], v[176:179], v[62:65]
	v_mfma_f32_16x16x32_bf16 v[58:61], v[168:171], v[176:179], v[58:61]
	v_mfma_f32_16x16x32_bf16 v[54:57], v[160:163], v[184:187], v[54:57]
	v_mfma_f32_16x16x32_bf16 v[46:49], v[168:171], v[184:187], v[46:49]
	v_mfma_f32_16x16x32_bf16 v[38:41], v[160:163], v[192:195], v[38:41]
	v_mfma_f32_16x16x32_bf16 v[30:33], v[168:171], v[192:195], v[30:33]
	v_mfma_f32_16x16x32_bf16 v[22:25], v[160:163], v[206:209], v[22:25]
	v_mfma_f32_16x16x32_bf16 v[14:17], v[168:171], v[206:209], v[14:17]
	s_setprio 0
	s_barrier
; #define PG8_STAGE(bufoff, gbase, voff) do { _Pragma("unroll") for (int _i = 0; _i < 2; ++_i) \
;         __builtin_amdgcn_global_load_lds((const unsigned*)((const char*)(gbase) + (voff)[_i]), (LAS unsigned*)(lds + (bufoff) + ldsw + _i * 8192), 16, 0, 0); } while (0)
; #define PG8_LDA(dst, b, h) do { _Pragma("unroll") for (int m = 0; m < 4; ++m) _Pragma("unroll") for (int k = 0; k < 2; ++k) dst[m][k] = *(const LAS bf16x8*)(lds + PG8_SA(b, h) + aoff + m * 2048 + k * 1024); } while (0)
; #define PG8_LDB(dst, b, h) do { _Pragma("unroll") for (int n = 0; n < 2; ++n) _Pragma("unroll") for (int k = 0; k < 2; ++k) dst[n][k] = *(const LAS bf16x8*)(lds + PG8_SB(b, h) + boff + n * 2048 + k * 1024); } while (0)
; #define PG8_MMA(ai, bj, At, Bt) do { __builtin_amdgcn_s_setprio(1); _Pragma("unroll") for (int m = 0; m < 4; ++m) _Pragma("unroll") for (int n = 0; n < 2; ++n) _Pragma("unroll") for (int k = 0; k < 2; ++k) \
;         acc[ai][bj][m][n] = __builtin_amdgcn_mfma_f32_16x16x32_bf16(Bt[n][k], At[m][k], acc[ai][bj][m][n], 0, 0, 0); __builtin_amdgcn_s_setprio(0); } while (0)
; #define PG8_WAIT_V(n) asm volatile("s_waitcnt vmcnt(" #n ")" ::: "memory")
; #define PG8_WAIT_L(n) asm volatile("s_waitcnt lgkmcnt(" #n ")" ::: "memory")
; #define PG8_BAR __builtin_amdgcn_s_barrier()
; #define PG8_SCHED __builtin_amdgcn_sched_barrier(0)
; template <class Epi>
; __device__ __forceinline__ void gemm_phase(LAS unsigned char* lds, const Gemm g, const StaticOrder& S, const Epi& E) {
;     ...
;             PG8_STAGE(PG8_SB(0, 1), b2 + hB, voffB);
;             PG8_WAIT_V(6); PG8_BAR; PG8_MMA(1, 1, At, B1); PG8_BAR;
;             PG8_LDB(B0, 1, 0); PG8_SCHED; PG8_LDA(At, 1, 0); PG8_STAGE(PG8_SA(0, 1), a2 + hA, voffA);
;             PG8_WAIT_L(8); PG8_BAR; PG8_WAIT_L(0); PG8_MMA(0, 0, At, B0); PG8_BAR; PG8_SCHED;
;             PG8_LDB(B1, 1, 1); PG8_STAGE(PG8_SB(1, 0), b3, voffB);
;             PG8_BAR; PG8_WAIT_L(0); PG8_MMA(0, 1, At, B1); PG8_BAR;
;             PG8_LDA(At, 1, 1); PG8_STAGE(PG8_SA(1, 0), a3, voffA);
;             PG8_BAR; PG8_WAIT_L(0); PG8_MMA(1, 0, At, B0); PG8_BAR; PG8_SCHED;
	s_add_u32 s68, s48, 0x40000
	s_addc_u32 s69, s49, 0
	s_add_i32 s67, s70, s33
	v_lshl_add_u64 v[156:157], s[68:69], 0, v[0:1]
	s_mov_b32 m0, s67
	s_nop 0
	global_load_lds_dwordx4 v[156:157], off
	v_lshl_add_u64 v[156:157], s[68:69], 0, v[134:135]
	s_add_i32 m0, s67, 0x2000
	s_nop 0
	global_load_lds_dwordx4 v[156:157], off
	s_waitcnt vmcnt(6)
	s_barrier
	s_setprio 1
	v_mfma_f32_16x16x32_bf16 v[50:53], v[210:213], v[172:175], v[50:53]
	v_mfma_f32_16x16x32_bf16 v[42:45], v[218:221], v[172:175], v[42:45]
	v_mfma_f32_16x16x32_bf16 v[34:37], v[210:213], v[180:183], v[34:37]
	v_mfma_f32_16x16x32_bf16 v[26:29], v[218:221], v[180:183], v[26:29]
	v_mfma_f32_16x16x32_bf16 v[18:21], v[210:213], v[188:191], v[18:21]
	v_mfma_f32_16x16x32_bf16 v[10:13], v[218:221], v[188:191], v[10:13]
	v_mfma_f32_16x16x32_bf16 v[6:9], v[210:213], v[202:205], v[6:9]
	v_mfma_f32_16x16x32_bf16 v[2:5], v[218:221], v[202:205], v[2:5]
	v_mfma_f32_16x16x32_bf16 v[50:53], v[214:217], v[176:179], v[50:53]
	v_mfma_f32_16x16x32_bf16 v[42:45], v[222:225], v[176:179], v[42:45]
	v_mfma_f32_16x16x32_bf16 v[34:37], v[214:217], v[184:187], v[34:37]
	v_mfma_f32_16x16x32_bf16 v[26:29], v[222:225], v[184:187], v[26:29]
	v_mfma_f32_16x16x32_bf16 v[18:21], v[214:217], v[192:195], v[18:21]
	v_mfma_f32_16x16x32_bf16 v[10:13], v[222:225], v[192:195], v[10:13]
	v_mfma_f32_16x16x32_bf16 v[6:9], v[214:217], v[206:209], v[6:9]
	v_mfma_f32_16x16x32_bf16 v[2:5], v[222:225], v[206:209], v[2:5]
	s_setprio 0
	s_add_i32 s67, 0, 0x18000
	v_add_u32_e32 v151, s67, v143
	s_barrier
	ds_read_b128 v[156:159], v151
	ds_read_b128 v[160:163], v151 offset:1024
	ds_read_b128 v[164:167], v151 offset:2048
	ds_read_b128 v[168:171], v151 offset:3072
	s_add_u32 s50, s50, 0x40000
	s_addc_u32 s51, s51, 0
	s_mov_b32 m0, s55
	v_lshl_add_u64 v[210:211], s[50:51], 0, v[130:131]
	ds_read_b128 v[172:175], v149 offset:32768
	ds_read_b128 v[176:179], v149 offset:33792
	ds_read_b128 v[180:183], v149 offset:34816
	ds_read_b128 v[184:187], v149 offset:35840
	ds_read_b128 v[188:191], v149 offset:36864
	ds_read_b128 v[192:195], v149 offset:37888
	ds_read_b128 v[202:205], v149 offset:38912
	ds_read_b128 v[206:209], v149 offset:39936
	global_load_lds_dwordx4 v[210:211], off
	v_lshl_add_u64 v[210:211], s[50:51], 0, v[132:133]
	s_mov_b32 m0, s56
	s_nop 0
	global_load_lds_dwordx4 v[210:211], off
	s_waitcnt lgkmcnt(8)
	s_barrier
	s_waitcnt lgkmcnt(0)
	s_setprio 1
	s_waitcnt lgkmcnt(0)
	v_mfma_f32_16x16x32_bf16 v[126:129], v[156:159], v[172:175], v[126:129]
	v_mfma_f32_16x16x32_bf16 v[122:125], v[164:167], v[172:175], v[122:125]
	v_mfma_f32_16x16x32_bf16 v[118:121], v[156:159], v[180:183], v[118:121]
	v_mfma_f32_16x16x32_bf16 v[110:113], v[164:167], v[180:183], v[110:113]
	v_mfma_f32_16x16x32_bf16 v[102:105], v[156:159], v[188:191], v[102:105]
	v_mfma_f32_16x16x32_bf16 v[94:97], v[164:167], v[188:191], v[94:97]
	v_mfma_f32_16x16x32_bf16 v[86:89], v[156:159], v[202:205], v[86:89]
	v_mfma_f32_16x16x32_bf16 v[78:81], v[164:167], v[202:205], v[78:81]
	v_mfma_f32_16x16x32_bf16 v[126:129], v[160:163], v[176:179], v[126:129]
	v_mfma_f32_16x16x32_bf16 v[122:125], v[168:171], v[176:179], v[122:125]
	v_mfma_f32_16x16x32_bf16 v[118:121], v[160:163], v[184:187], v[118:121]
	v_mfma_f32_16x16x32_bf16 v[110:113], v[168:171], v[184:187], v[110:113]
	v_mfma_f32_16x16x32_bf16 v[102:105], v[160:163], v[192:195], v[102:105]
	v_mfma_f32_16x16x32_bf16 v[94:97], v[168:171], v[192:195], v[94:97]
	v_mfma_f32_16x16x32_bf16 v[86:89], v[160:163], v[206:209], v[86:89]
	v_mfma_f32_16x16x32_bf16 v[78:81], v[168:171], v[206:209], v[78:81]
	s_setprio 0
	s_barrier
	s_add_i32 s50, 0, 0x1c000
	s_add_i32 s51, s67, s33
	v_add_u32_e32 v151, s50, v143
	v_lshl_add_u64 v[226:227], v[226:227], 0, s[34:35]
	s_mov_b32 m0, s51
	ds_read_b128 v[210:213], v151
	ds_read_b128 v[214:217], v151 offset:1024
	ds_read_b128 v[218:221], v151 offset:2048
	ds_read_b128 v[222:225], v151 offset:3072
	global_load_lds_dwordx4 v[226:227], off
	v_lshl_add_u64 v[226:227], v[240:241], 0, s[34:35]
	s_add_i32 m0, s51, 0x2000
	s_nop 0
	global_load_lds_dwordx4 v[226:227], off
	s_barrier
	s_waitcnt lgkmcnt(0)
	s_setprio 1
	s_waitcnt lgkmcnt(0)
	v_mfma_f32_16x16x32_bf16 v[114:117], v[210:213], v[172:175], v[114:117]
	v_mfma_f32_16x16x32_bf16 v[106:109], v[218:221], v[172:175], v[106:109]
	v_mfma_f32_16x16x32_bf16 v[98:101], v[210:213], v[180:183], v[98:101]
	v_mfma_f32_16x16x32_bf16 v[90:93], v[218:221], v[180:183], v[90:93]
	v_mfma_f32_16x16x32_bf16 v[82:85], v[210:213], v[188:191], v[82:85]
	v_mfma_f32_16x16x32_bf16 v[74:77], v[218:221], v[188:191], v[74:77]
	v_mfma_f32_16x16x32_bf16 v[70:73], v[210:213], v[202:205], v[70:73]
	v_mfma_f32_16x16x32_bf16 v[66:69], v[218:221], v[202:205], v[66:69]
	v_mfma_f32_16x16x32_bf16 v[114:117], v[214:217], v[176:179], v[114:117]
	v_mfma_f32_16x16x32_bf16 v[106:109], v[222:225], v[176:179], v[106:109]
	v_mfma_f32_16x16x32_bf16 v[98:101], v[214:217], v[184:187], v[98:101]
	v_mfma_f32_16x16x32_bf16 v[90:93], v[222:225], v[184:187], v[90:93]
	v_mfma_f32_16x16x32_bf16 v[82:85], v[214:217], v[192:195], v[82:85]
	v_mfma_f32_16x16x32_bf16 v[74:77], v[222:225], v[192:195], v[74:77]
	v_mfma_f32_16x16x32_bf16 v[70:73], v[214:217], v[206:209], v[70:73]
	v_mfma_f32_16x16x32_bf16 v[66:69], v[222:225], v[206:209], v[66:69]
	s_setprio 0
	s_mov_b32 m0, s58
	v_lshl_add_u64 v[226:227], v[242:243], 0, s[34:35]
	s_barrier
	ds_read_b128 v[172:175], v149 offset:49152
	ds_read_b128 v[176:179], v149 offset:50176
	ds_read_b128 v[180:183], v149 offset:51200
	ds_read_b128 v[184:187], v149 offset:52224
	ds_read_b128 v[188:191], v149 offset:53248
	ds_read_b128 v[192:195], v149 offset:54272
	ds_read_b128 v[202:205], v149 offset:55296
	ds_read_b128 v[206:209], v149 offset:56320
	global_load_lds_dwordx4 v[226:227], off
	v_lshl_add_u64 v[226:227], v[244:245], 0, s[34:35]
	s_mov_b32 m0, s59
	s_nop 0
	global_load_lds_dwordx4 v[226:227], off
	s_barrier
; #define PG8_STAGE(bufoff, gbase, voff) do { _Pragma("unroll") for (int _i = 0; _i < 2; ++_i) \
;         __builtin_amdgcn_global_load_lds((const unsigned*)((const char*)(gbase) + (voff)[_i]), (LAS unsigned*)(lds + (bufoff) + ldsw + _i * 8192), 16, 0, 0); } while (0)
; #define PG8_MMA(ai, bj, At, Bt) do { __builtin_amdgcn_s_setprio(1); _Pragma("unroll") for (int m = 0; m < 4; ++m) _Pragma("unroll") for (int n = 0; n < 2; ++n) _Pragma("unroll") for (int k = 0; k < 2; ++k) \
;         acc[ai][bj][m][n] = __builtin_amdgcn_mfma_f32_16x16x32_bf16(Bt[n][k], At[m][k], acc[ai][bj][m][n], 0, 0, 0); __builtin_amdgcn_s_setprio(0); } while (0)
; #define PG8_WAIT_V(n) asm volatile("s_waitcnt vmcnt(" #n ")" ::: "memory")
; #define PG8_WAIT_L(n) asm volatile("s_waitcnt lgkmcnt(" #n ")" ::: "memory")
; #define PG8_BAR __builtin_amdgcn_s_barrier()
; #define PG8_SCHED __builtin_amdgcn_sched_barrier(0)
; __device__ __forceinline__ u32x4 pack8(const f32x4 a, const f32x4 b) { u32x4 w; w.x = cvt_pk_bf16(a[0], a[1]); w.y = cvt_pk_bf16(a[2], a[3]); w.z = cvt_pk_bf16(b[0], b[1]); w.w = cvt_pk_bf16(b[2], b[3]); return w; }
; template <class Epi>
; __device__ __forceinline__ void gemm_phase(LAS unsigned char* lds, const Gemm g, const StaticOrder& S, const Epi& E) {
;     ...
;             PG8_BAR; PG8_WAIT_L(0); PG8_MMA(1, 0, At, B0); PG8_BAR; PG8_SCHED;
;             PG8_STAGE(PG8_SB(1, 1), b3 + hB, voffB);
;             PG8_WAIT_V(6); PG8_BAR; PG8_MMA(1, 1, At, B1); PG8_BAR;
;         }
;         if constexpr (Epi::HAS_PRE) { E(acc, cur, wr, wc, fr, fq, pre); if (has_next) E.pre(pre, nxt, wr, fr); } else E(acc, cur, wr, wc, fr, fq);
;         if (!has_next) break;
;     __device__ __forceinline__ void operator()(const Acc& acc, const Unit& u, int wr, int wc, int fr, int fq, const RsPre& pr) const {
;         asm volatile("" : "+v"(fr), "+v"(fq));
;         const int row0 = u.pm * 256 + wr * 64 + fr, col0 = u.pn * 256 + wc * 32 + 8 * fq;
;         const float (&rs)[2][4] = pr.rs;
; #pragma unroll
;         for (int ai = 0; ai < 2; ++ai)
; #pragma unroll
;             for (int m = 0; m < 4; ++m) { bf16_t* rowp = O + (size_t)(row0 + ai * 128 + m * 16) * ldc + col0;
; #pragma unroll
;                 for (int bj = 0; bj < 2; ++bj) *(u32x4*)(rowp + bj * 128) = pack8(acc[ai][bj][m][0] * rs[ai][m], acc[ai][bj][m][1] * rs[ai][m]); }
	s_waitcnt lgkmcnt(0)
	s_setprio 1
	s_waitcnt lgkmcnt(0)
	v_mfma_f32_16x16x32_bf16 v[62:65], v[156:159], v[172:175], v[62:65]
	v_mfma_f32_16x16x32_bf16 v[58:61], v[164:167], v[172:175], v[58:61]
	v_mfma_f32_16x16x32_bf16 v[54:57], v[156:159], v[180:183], v[54:57]
	v_mfma_f32_16x16x32_bf16 v[46:49], v[164:167], v[180:183], v[46:49]
	v_mfma_f32_16x16x32_bf16 v[38:41], v[156:159], v[188:191], v[38:41]
	v_mfma_f32_16x16x32_bf16 v[30:33], v[164:167], v[188:191], v[30:33]
	v_mfma_f32_16x16x32_bf16 v[22:25], v[156:159], v[202:205], v[22:25]
	v_mfma_f32_16x16x32_bf16 v[14:17], v[164:167], v[202:205], v[14:17]
	v_mfma_f32_16x16x32_bf16 v[62:65], v[160:163], v[176:179], v[62:65]
	v_mfma_f32_16x16x32_bf16 v[58:61], v[168:171], v[176:179], v[58:61]
	v_mfma_f32_16x16x32_bf16 v[54:57], v[160:163], v[184:187], v[54:57]
	v_mfma_f32_16x16x32_bf16 v[46:49], v[168:171], v[184:187], v[46:49]
	v_mfma_f32_16x16x32_bf16 v[38:41], v[160:163], v[192:195], v[38:41]
	v_mfma_f32_16x16x32_bf16 v[30:33], v[168:171], v[192:195], v[30:33]
	v_mfma_f32_16x16x32_bf16 v[22:25], v[160:163], v[206:209], v[22:25]
	v_mfma_f32_16x16x32_bf16 v[14:17], v[168:171], v[206:209], v[14:17]
	s_setprio 0
	s_barrier
	s_add_u32 s48, s48, 0x40080
	s_addc_u32 s49, s49, 0
	s_add_i32 s50, s50, s33
	v_lshl_add_u64 v[156:157], s[48:49], 0, v[0:1]
	s_mov_b32 m0, s50
	s_nop 0
	global_load_lds_dwordx4 v[156:157], off
	v_lshl_add_u64 v[156:157], s[48:49], 0, v[134:135]
	s_add_i32 m0, s50, 0x2000
	s_nop 0
	global_load_lds_dwordx4 v[156:157], off
	s_waitcnt vmcnt(6)
	s_barrier
	s_setprio 1
	v_mfma_f32_16x16x32_bf16 v[50:53], v[210:213], v[172:175], v[50:53]
	v_mfma_f32_16x16x32_bf16 v[42:45], v[218:221], v[172:175], v[42:45]
	v_mfma_f32_16x16x32_bf16 v[34:37], v[210:213], v[180:183], v[34:37]
	v_mfma_f32_16x16x32_bf16 v[26:29], v[218:221], v[180:183], v[26:29]
	v_mfma_f32_16x16x32_bf16 v[18:21], v[210:213], v[188:191], v[18:21]
	v_mfma_f32_16x16x32_bf16 v[10:13], v[218:221], v[188:191], v[10:13]
	v_mfma_f32_16x16x32_bf16 v[6:9], v[210:213], v[202:205], v[6:9]
	v_mfma_f32_16x16x32_bf16 v[2:5], v[218:221], v[202:205], v[2:5]
	v_mfma_f32_16x16x32_bf16 v[50:53], v[214:217], v[176:179], v[50:53]
	v_mfma_f32_16x16x32_bf16 v[42:45], v[222:225], v[176:179], v[42:45]
	v_mfma_f32_16x16x32_bf16 v[34:37], v[214:217], v[184:187], v[34:37]
	v_mfma_f32_16x16x32_bf16 v[26:29], v[222:225], v[184:187], v[26:29]
	v_mfma_f32_16x16x32_bf16 v[18:21], v[214:217], v[192:195], v[18:21]
	v_mfma_f32_16x16x32_bf16 v[10:13], v[222:225], v[192:195], v[10:13]
	v_mfma_f32_16x16x32_bf16 v[6:9], v[214:217], v[206:209], v[6:9]
	v_mfma_f32_16x16x32_bf16 v[2:5], v[222:225], v[206:209], v[2:5]
	s_setprio 0
	s_add_i32 s66, s66, 2
	s_add_u32 s46, s46, 0x100
	s_addc_u32 s47, s47, 0
	s_add_u32 s64, s64, 0x100
	s_addc_u32 s65, s65, 0
	s_cmp_gt_u32 s66, 13
	s_barrier
	s_cbranch_scc0 .LBB0_623
	v_mov_b32_e32 v151, v137
	v_mov_b32_e32 v153, v139
	s_lshl_b32 s15, s44, 8
	s_add_i32 s15, s15, s52
	v_add_u32_e32 v151, s15, v151
	s_lshl_b32 s15, s45, 8
	s_or_b32 s15, s15, s57
	v_lshl_add_u32 v158, v153, 3, s15
	v_lshlrev_b32_e32 v158, 1, v158
	v_mad_u32_u24 v160, v151, s96, v158
	s_waitcnt vmcnt(0)
	v_pk_mul_f32 v[128:129], v[154:155], v[128:129] op_sel_hi:[0,1]
	v_pk_mul_f32 v[126:127], v[154:155], v[126:127] op_sel_hi:[0,1]
	v_pk_mul_f32 v[162:163], v[154:155], v[124:125] op_sel_hi:[0,1]
	v_pk_mul_f32 v[124:125], v[154:155], v[122:123] op_sel_hi:[0,1]
	v_cvt_pk_bf16_f32 v122, v126, v127
	v_cvt_pk_bf16_f32 v123, v128, v129
	v_cvt_pk_bf16_f32 v124, v124, v125
	v_cvt_pk_bf16_f32 v125, v162, v163
	global_store_dwordx4 v160, v[122:125], s[20:21]
	v_pk_mul_f32 v[116:117], v[154:155], v[116:117] op_sel_hi:[0,1]
	v_pk_mul_f32 v[114:115], v[154:155], v[114:115] op_sel_hi:[0,1]
	v_pk_mul_f32 v[122:123], v[154:155], v[108:109] op_sel_hi:[0,1]
	v_pk_mul_f32 v[108:109], v[154:155], v[106:107] op_sel_hi:[0,1]
	v_cvt_pk_bf16_f32 v106, v114, v115
	v_cvt_pk_bf16_f32 v107, v116, v117
	v_cvt_pk_bf16_f32 v108, v108, v109
	v_cvt_pk_bf16_f32 v109, v122, v123
	global_store_dwordx4 v160, v[106:109], s[20:21] offset:256
	v_pk_mul_f32 v[112:113], v[152:153], v[112:113] op_sel_hi:[0,1]
	v_pk_mul_f32 v[110:111], v[152:153], v[110:111] op_sel_hi:[0,1]
	v_add_u32_e32 v114, 0x22000, v160
	v_pk_mul_f32 v[108:109], v[152:153], v[120:121] op_sel_hi:[0,1]
	v_pk_mul_f32 v[106:107], v[152:153], v[118:119] op_sel_hi:[0,1]
	v_cvt_pk_bf16_f32 v106, v106, v107
	v_cvt_pk_bf16_f32 v107, v108, v109
	v_cvt_pk_bf16_f32 v108, v110, v111
	v_cvt_pk_bf16_f32 v109, v112, v113
	global_store_dwordx4 v114, v[106:109], s[20:21]
	v_pk_mul_f32 v[100:101], v[152:153], v[100:101] op_sel_hi:[0,1]
	v_pk_mul_f32 v[98:99], v[152:153], v[98:99] op_sel_hi:[0,1]
	v_pk_mul_f32 v[106:107], v[152:153], v[92:93] op_sel_hi:[0,1]
	v_pk_mul_f32 v[92:93], v[152:153], v[90:91] op_sel_hi:[0,1]
	v_cvt_pk_bf16_f32 v90, v98, v99
	v_cvt_pk_bf16_f32 v91, v100, v101
	v_cvt_pk_bf16_f32 v92, v92, v93
	v_cvt_pk_bf16_f32 v93, v106, v107
	global_store_dwordx4 v114, v[90:93], s[20:21] offset:256
	v_pk_mul_f32 v[96:97], v[150:151], v[96:97] op_sel_hi:[0,1]
	v_pk_mul_f32 v[94:95], v[150:151], v[94:95] op_sel_hi:[0,1]
	v_add_u32_e32 v98, 0x44000, v160
	v_pk_mul_f32 v[92:93], v[150:151], v[104:105] op_sel_hi:[0,1]
	v_pk_mul_f32 v[90:91], v[150:151], v[102:103] op_sel_hi:[0,1]
	v_cvt_pk_bf16_f32 v90, v90, v91
	v_cvt_pk_bf16_f32 v91, v92, v93
	v_cvt_pk_bf16_f32 v92, v94, v95
	v_cvt_pk_bf16_f32 v93, v96, v97
	global_store_dwordx4 v98, v[90:93], s[20:21]
; __device__ __forceinline__ u32x4 pack8(const f32x4 a, const f32x4 b) { u32x4 w; w.x = cvt_pk_bf16(a[0], a[1]); w.y = cvt_pk_bf16(a[2], a[3]); w.z = cvt_pk_bf16(b[0], b[1]); w.w = cvt_pk_bf16(b[2], b[3]); return w; }
;     __device__ __forceinline__ void pre(RsPre& r, const Unit& u, int wr, int fr) const {
; #pragma unroll
;         for (int ai = 0; ai < 2; ++ai)
; #pragma unroll
;             for (int m = 0; m < 4; ++m) r.rs[ai][m] = rsv[u.pm * 256 + wr * 64 + fr + ai * 128 + m * 16]; }
;     __device__ __forceinline__ void operator()(const Acc& acc, const Unit& u, int wr, int wc, int fr, int fq, const RsPre& pr) const {
;     ...
; #pragma unroll
;         for (int ai = 0; ai < 2; ++ai)
; #pragma unroll
;             for (int m = 0; m < 4; ++m) { bf16_t* rowp = O + (size_t)(row0 + ai * 128 + m * 16) * ldc + col0;
; #pragma unroll
;                 for (int bj = 0; bj < 2; ++bj) *(u32x4*)(rowp + bj * 128) = pack8(acc[ai][bj][m][0] * rs[ai][m], acc[ai][bj][m][1] * rs[ai][m]); }
	v_pk_mul_f32 v[84:85], v[150:151], v[84:85] op_sel_hi:[0,1]
	v_pk_mul_f32 v[82:83], v[150:151], v[82:83] op_sel_hi:[0,1]
	v_pk_mul_f32 v[90:91], v[150:151], v[76:77] op_sel_hi:[0,1]
	v_pk_mul_f32 v[76:77], v[150:151], v[74:75] op_sel_hi:[0,1]
	v_cvt_pk_bf16_f32 v74, v82, v83
	v_cvt_pk_bf16_f32 v75, v84, v85
	v_cvt_pk_bf16_f32 v76, v76, v77
	v_cvt_pk_bf16_f32 v77, v90, v91
	global_store_dwordx4 v98, v[74:77], s[20:21] offset:256
	v_pk_mul_f32 v[80:81], v[148:149], v[80:81] op_sel_hi:[0,1]
	v_pk_mul_f32 v[78:79], v[148:149], v[78:79] op_sel_hi:[0,1]
	v_add_u32_e32 v82, 0x66000, v160
	v_pk_mul_f32 v[76:77], v[148:149], v[88:89] op_sel_hi:[0,1]
	v_pk_mul_f32 v[74:75], v[148:149], v[86:87] op_sel_hi:[0,1]
	v_cvt_pk_bf16_f32 v74, v74, v75
	v_cvt_pk_bf16_f32 v75, v76, v77
	v_cvt_pk_bf16_f32 v76, v78, v79
	v_cvt_pk_bf16_f32 v77, v80, v81
	global_store_dwordx4 v82, v[74:77], s[20:21]
	v_pk_mul_f32 v[72:73], v[148:149], v[72:73] op_sel_hi:[0,1]
	v_pk_mul_f32 v[70:71], v[148:149], v[70:71] op_sel_hi:[0,1]
	v_pk_mul_f32 v[74:75], v[148:149], v[68:69] op_sel_hi:[0,1]
	v_pk_mul_f32 v[68:69], v[148:149], v[66:67] op_sel_hi:[0,1]
	v_cvt_pk_bf16_f32 v66, v70, v71
	v_cvt_pk_bf16_f32 v67, v72, v73
	v_cvt_pk_bf16_f32 v68, v68, v69
	v_cvt_pk_bf16_f32 v69, v74, v75
	global_store_dwordx4 v82, v[66:69], s[20:21] offset:256
	v_pk_mul_f32 v[64:65], v[142:143], v[64:65] op_sel_hi:[0,1]
	v_pk_mul_f32 v[62:63], v[142:143], v[62:63] op_sel_hi:[0,1]
	v_pk_mul_f32 v[68:69], v[142:143], v[60:61] op_sel_hi:[0,1]
	v_pk_mul_f32 v[60:61], v[142:143], v[58:59] op_sel_hi:[0,1]
	v_add_u32_e32 v66, 0x110000, v160
	v_cvt_pk_bf16_f32 v58, v62, v63
	v_cvt_pk_bf16_f32 v59, v64, v65
	v_cvt_pk_bf16_f32 v60, v60, v61
	v_cvt_pk_bf16_f32 v61, v68, v69
	global_store_dwordx4 v66, v[58:61], s[20:21]
	v_pk_mul_f32 v[52:53], v[142:143], v[52:53] op_sel_hi:[0,1]
	v_pk_mul_f32 v[50:51], v[142:143], v[50:51] op_sel_hi:[0,1]
	v_pk_mul_f32 v[58:59], v[142:143], v[44:45] op_sel_hi:[0,1]
	v_pk_mul_f32 v[44:45], v[142:143], v[42:43] op_sel_hi:[0,1]
	v_cvt_pk_bf16_f32 v42, v50, v51
	v_cvt_pk_bf16_f32 v43, v52, v53
	v_cvt_pk_bf16_f32 v44, v44, v45
	v_cvt_pk_bf16_f32 v45, v58, v59
	global_store_dwordx4 v66, v[42:45], s[20:21] offset:256
	v_pk_mul_f32 v[48:49], v[140:141], v[48:49] op_sel_hi:[0,1]
	v_pk_mul_f32 v[46:47], v[140:141], v[46:47] op_sel_hi:[0,1]
	v_add_u32_e32 v50, 0x132000, v160
	v_pk_mul_f32 v[44:45], v[140:141], v[56:57] op_sel_hi:[0,1]
	v_pk_mul_f32 v[42:43], v[140:141], v[54:55] op_sel_hi:[0,1]
	v_cvt_pk_bf16_f32 v42, v42, v43
	v_cvt_pk_bf16_f32 v43, v44, v45
	v_cvt_pk_bf16_f32 v44, v46, v47
	v_cvt_pk_bf16_f32 v45, v48, v49
	global_store_dwordx4 v50, v[42:45], s[20:21]
	v_pk_mul_f32 v[36:37], v[140:141], v[36:37] op_sel_hi:[0,1]
	v_pk_mul_f32 v[34:35], v[140:141], v[34:35] op_sel_hi:[0,1]
	v_pk_mul_f32 v[42:43], v[140:141], v[28:29] op_sel_hi:[0,1]
	v_pk_mul_f32 v[28:29], v[140:141], v[26:27] op_sel_hi:[0,1]
	v_cvt_pk_bf16_f32 v26, v34, v35
	v_cvt_pk_bf16_f32 v27, v36, v37
	v_cvt_pk_bf16_f32 v28, v28, v29
	v_cvt_pk_bf16_f32 v29, v42, v43
	global_store_dwordx4 v50, v[26:29], s[20:21] offset:256
	v_pk_mul_f32 v[32:33], v[138:139], v[32:33] op_sel_hi:[0,1]
	v_pk_mul_f32 v[30:31], v[138:139], v[30:31] op_sel_hi:[0,1]
	v_add_u32_e32 v34, 0x154000, v160
	v_pk_mul_f32 v[28:29], v[138:139], v[40:41] op_sel_hi:[0,1]
	v_pk_mul_f32 v[26:27], v[138:139], v[38:39] op_sel_hi:[0,1]
	v_cvt_pk_bf16_f32 v26, v26, v27
	v_cvt_pk_bf16_f32 v27, v28, v29
	v_cvt_pk_bf16_f32 v28, v30, v31
	v_cvt_pk_bf16_f32 v29, v32, v33
	global_store_dwordx4 v34, v[26:29], s[20:21]
	v_pk_mul_f32 v[20:21], v[138:139], v[20:21] op_sel_hi:[0,1]
	v_pk_mul_f32 v[18:19], v[138:139], v[18:19] op_sel_hi:[0,1]
	v_pk_mul_f32 v[26:27], v[138:139], v[12:13] op_sel_hi:[0,1]
	v_pk_mul_f32 v[12:13], v[138:139], v[10:11] op_sel_hi:[0,1]
	v_cvt_pk_bf16_f32 v10, v18, v19
	v_cvt_pk_bf16_f32 v11, v20, v21
	v_cvt_pk_bf16_f32 v12, v12, v13
	v_cvt_pk_bf16_f32 v13, v26, v27
	global_store_dwordx4 v34, v[10:13], s[20:21] offset:256
	v_pk_mul_f32 v[16:17], v[136:137], v[16:17] op_sel_hi:[0,1]
	v_pk_mul_f32 v[14:15], v[136:137], v[14:15] op_sel_hi:[0,1]
	v_add_u32_e32 v18, 0x176000, v160
	v_pk_mul_f32 v[12:13], v[136:137], v[24:25] op_sel_hi:[0,1]
	v_pk_mul_f32 v[10:11], v[136:137], v[22:23] op_sel_hi:[0,1]
	v_cvt_pk_bf16_f32 v10, v10, v11
	v_cvt_pk_bf16_f32 v11, v12, v13
	v_cvt_pk_bf16_f32 v12, v14, v15
	v_cvt_pk_bf16_f32 v13, v16, v17
	global_store_dwordx4 v18, v[10:13], s[20:21]
	v_pk_mul_f32 v[8:9], v[136:137], v[8:9] op_sel_hi:[0,1]
	v_pk_mul_f32 v[6:7], v[136:137], v[6:7] op_sel_hi:[0,1]
	v_pk_mul_f32 v[10:11], v[136:137], v[4:5] op_sel_hi:[0,1]
	v_pk_mul_f32 v[4:5], v[136:137], v[2:3] op_sel_hi:[0,1]
	v_cvt_pk_bf16_f32 v2, v6, v7
	v_cvt_pk_bf16_f32 v3, v8, v9
	v_cvt_pk_bf16_f32 v4, v4, v5
	v_cvt_pk_bf16_f32 v5, v10, v11
	s_mov_b64 s[44:45], -1
	s_and_b64 vcc, vcc, exec
	global_store_dwordx4 v18, v[2:5], s[20:21] offset:256
	s_cbranch_vccz .LBB0_615
	s_nop 0
	v_lshl_add_u32 v2, s22, 8, v141
	v_ashrrev_i32_e32 v3, 31, v2
	v_lshl_add_u64 v[2:3], v[2:3], 2, s[10:11]
	global_load_dword v154, v[2:3], off
	global_load_dword v152, v[2:3], off offset:64
	global_load_dword v150, v[2:3], off offset:128
	global_load_dword v148, v[2:3], off offset:192
	global_load_dword v142, v[2:3], off offset:512
	global_load_dword v140, v[2:3], off offset:576
	global_load_dword v138, v[2:3], off offset:640
	global_load_dword v136, v[2:3], off offset:704
	s_mov_b64 s[44:45], 0
	s_branch .LBB0_615
